# last partial round of in-proj/up GEMMs split into 128-row half tiles over all CUs
# baseline (speedup 1.0000x reference)
; #define LAS __attribute__((address_space(3)))
;     __host__ __device__ bool next(int i, Unit& u) const {
;         const long L = (long)i * G + c; if (L >= nwg) return false;
;         int wgid = (int)L; { const int q = nwg / NXCD, r = nwg % NXCD, xcd = wgid % NXCD, off = wgid / NXCD; wgid = (xcd < r ? xcd * (q + 1) : r * (q + 1) + (xcd - r) * q) + off; }
;         const int nig = WGM * nN, gid = wgid / nig, fm = gid * WGM, gsz = (nM - fm) < WGM ? (nM - fm) : WGM;
;         u.pm = fm + ((wgid % nig) % gsz); u.pn = (wgid % nig) / gsz; return true;
; __global__ void __launch_bounds__(512, 2) fwd_kernel(Args a) {
;     ...
;             pg8::Gemm g{XBF, Bt, T, N, D}; pg8::StaticOrder S; S.init(T, N, G, (int)blockIdx.x);
;             pg8::EpiBf16Ln E{(k == 0) ? PROJ : Z, N, (k == 0) ? S2 : S1, CD + (size_t)l * 32768 + (k == 0 ? 0 : 10240), CD + (size_t)l * 32768 + (k == 0 ? 5120 : 21504), lds + 131072, (k == 0 && l == 0) ? 0 : 1};
;             if ((tid & 63) == 0) *((LAS int*)(lds + 131072 + 14336) + (tid >> 6)) = -1;
.LBB0_361:
	s_mov_b32 s100, 0
	s_mov_b32 s101, 0
	v_and_b32_e32 v0, 63, v223
	v_cmp_eq_u32_e32 vcc, 0, v0
	s_and_saveexec_b64 s[0:1], vcc
	v_ashrrev_i32_e32 v0, 4, v223
	v_add_u32_e32 v0, 0, v0
	v_add_u32_e32 v0, 0x23800, v0
	ds_write_b32 v0, v218
	s_or_b64 exec, exec, s[0:1]
	s_cmp_eq_u32 s62, 0
	s_cselect_b64 s[36:37], -1, 0
	s_and_b64 s[0:1], s[36:37], exec
	s_movk_i32 s0, 0x2c00
	s_cselect_b32 s52, 0x1400, s0
	s_lshr_b32 s53, s52, 5
	v_cvt_f32_u32_e32 v8, s53
	s_lshr_b32 s28, s52, 3
	s_cmp_lt_i32 s99, s28
	s_cselect_b64 s[30:31], -1, 0
	s_cmp_ge_i32 s99, s28
	v_readfirstlane_b32 s4, v223
	s_cbranch_scc1 .LBB0_365
	v_rcp_iflag_f32_e32 v0, v8
	s_lshr_b32 s0, s52, 6
	v_readlane_b32 s1, v254, 8
	s_or_b32 s0, s0, s1
	v_mul_f32_e32 v0, 0x4f7ffffe, v0
	v_cvt_u32_f32_e32 v0, v0
	v_readlane_b32 s1, v254, 7
	s_sub_i32 s6, 0, s53
	s_mul_i32 s0, s0, s1
	v_readfirstlane_b32 s7, v0
	v_readlane_b32 s1, v253, 61
	s_mul_i32 s6, s6, s7
	s_add_i32 s0, s0, s1
	s_mul_hi_u32 s6, s7, s6
	s_abs_i32 s5, s0
	s_add_i32 s7, s7, s6
	s_mul_hi_u32 s6, s5, s7
	s_mul_i32 s7, s6, s53
	s_sub_i32 s5, s5, s7
	s_ashr_i32 s1, s0, 31
	s_add_i32 s7, s6, 1
	s_sub_i32 s8, s5, s53
	s_cmp_ge_u32 s5, s53
	s_cselect_b32 s6, s7, s6
	s_cselect_b32 s5, s8, s5
	s_add_i32 s7, s6, 1
	s_cmp_ge_u32 s5, s53
	s_cselect_b32 s5, s7, s6
	s_xor_b32 s5, s5, s1
	s_sub_i32 s1, s5, s1
	s_lshl_b32 s5, s1, 3
	s_sub_i32 s6, 32, s5
	s_min_i32 s6, s6, 8
	s_sext_i32_i16 s7, s6
	v_cvt_f32_i32_e32 v0, s7
	s_mul_i32 s1, s1, s53
	s_sub_i32 s8, s0, s1
	s_sext_i32_i16 s0, s8
	v_cvt_f32_i32_e32 v1, s0
	s_waitcnt lgkmcnt(0)
	v_rcp_iflag_f32_e32 v2, v0
	s_xor_b32 s0, s0, s7
	s_ashr_i32 s0, s0, 30
	s_or_b32 s7, s0, 1
	v_mul_f32_e32 v2, v1, v2
	v_trunc_f32_e32 v2, v2
	v_fma_f32 v1, -v2, v0, v1
	v_cvt_i32_f32_e32 v2, v2
	v_cmp_ge_f32_e64 s[0:1], |v1|, |v0|
	s_and_b64 s[0:1], s[0:1], exec
	s_cselect_b32 s0, s7, 0
	v_readfirstlane_b32 s1, v2
	s_add_i32 s1, s1, s0
	s_sext_i32_i16 s0, s1
	s_mul_i32 s1, s1, s6
	s_sub_i32 s1, s8, s1
	s_sext_i32_i16 s1, s1
	s_add_i32 s38, s5, s1

;     __host__ __device__ bool next(int i, Unit& u) const {
;         const long L = (long)i * G + c; if (L >= nwg) return false;
;         int wgid = (int)L; { const int q = nwg / NXCD, r = nwg % NXCD, xcd = wgid % NXCD, off = wgid / NXCD; wgid = (xcd < r ? xcd * (q + 1) : r * (q + 1) + (xcd - r) * q) + off; }
;         const int nig = WGM * nN, gid = wgid / nig, fm = gid * WGM, gsz = (nM - fm) < WGM ? (nM - fm) : WGM;
;         u.pm = fm + ((wgid % nig) % gsz); u.pn = (wgid % nig) / gsz; return true;
; template <class Epi, class Sched, bool ALIGN_EPI = false, bool SP2 = false>
; __device__ __forceinline__ void gemm_phase(PG8_LAS unsigned char* lds, const Gemm g, const Sched& S, const Epi& E, const int tid_in) {
;     ...
;         const bool has_next = S.next(ui + 1, nxt);
;         const char* nA = has_next ? (const char*)g.A + (size_t)nxt.pm * tstep : cA; const char* nB = has_next ? (const char*)g.Bt + (size_t)nxt.pn * tstep : cB;
;         for (int t = 0; t < nt; t += 2) {
;             const bool last = (t == nt - 2);
;             const char* a1 = cA + (size_t)(t + 1) * kstep;
;             const char* a2 = last ? nA : cA + (size_t)(t + 2) * kstep; const char* b2 = last ? nB : cB + (size_t)(t + 2) * kstep;
;             const char* a3 = a2 + kstep; const char* b3 = b2 + kstep;
.LBB0_370:
	s_mov_b32 s100, s101
	s_andn2_b64 vcc, exec, s[0:1]
	s_mov_b32 s0, s54
	s_mov_b32 s38, s56
	s_mov_b64 s[62:63], s[60:61]
	s_mov_b64 s[30:31], s[58:59]
	s_cbranch_vccz .LBB0_434
.LBB0_371:
	s_add_i32 s76, s76, 1
	v_readlane_b32 s1, v253, 52
	v_readlane_b32 s4, v252, 0
	s_mul_i32 s1, s76, s1
	s_mov_b32 s6, s4
	s_mul_hi_u32 s4, s76, s4
	s_add_i32 s4, s4, s1
	s_mul_i32 s1, s76, s6
	s_add_u32 s58, s1, s99
	v_readlane_b32 s1, v253, 51
	s_addc_u32 s59, s4, s1
	s_mov_b32 s101, 0
	s_and_b32 s4, s28, 0xff
	s_cmpk_lg_u32 s6, 0x100
	s_cbranch_scc1 .Lht_sched_done
	s_cmpk_lg_u32 s4, 0x80
	s_cbranch_scc1 .Lht_sched_done
	s_lshr_b32 s4, s28, 8
	s_cmp_lg_u32 s76, s4
	s_cbranch_scc1 .Lht_sched_done
	s_and_b32 s1, s99, 0x7f
	s_lshl_b32 s4, s4, 8
	s_add_i32 s58, s4, s1
	s_mov_b32 s59, 0
	s_lshr_b32 s1, s99, 7
	s_lshl_b32 s1, s1, 1
	s_or_b32 s101, s1, 1
.Lht_sched_done:
	v_mov_b64_e32 v[0:1], s[28:29]
	v_cmp_ge_i64_e32 vcc, s[58:59], v[0:1]
	v_cmp_lt_i64_e64 s[36:37], s[58:59], v[0:1]
	v_readlane_b32 s5, v252, 1
	s_cbranch_vccnz .LBB0_373
	s_ashr_i32 s1, s58, 31
	s_lshr_b32 s1, s1, 29
	s_add_i32 s1, s58, s1
	s_ashr_i32 s4, s1, 3
	s_and_b32 s1, s1, -8
	s_sub_i32 s1, s58, s1
	s_lshr_b32 s5, s1, 31
	s_or_b32 s5, s77, s5
	s_mul_i32 s1, s5, s1
	s_add_i32 s1, s1, s4
	s_abs_i32 s5, s1
	s_mul_hi_u32 s6, s5, s79
	s_mul_i32 s7, s6, s53
	s_sub_i32 s5, s5, s7
	s_ashr_i32 s4, s1, 31
	s_add_i32 s7, s6, 1
	s_sub_i32 s8, s5, s53
	s_cmp_ge_u32 s5, s53
	s_cselect_b32 s6, s7, s6
	s_cselect_b32 s5, s8, s5
	s_add_i32 s7, s6, 1
	s_cmp_ge_u32 s5, s53
	s_cselect_b32 s5, s7, s6
	s_xor_b32 s5, s5, s4
	s_sub_i32 s4, s5, s4
	s_lshl_b32 s5, s4, 3
	s_sub_i32 s6, 32, s5
	s_min_i32 s6, s6, 8
	s_abs_i32 s7, s6
	v_cvt_f32_u32_e32 v0, s7
	s_sub_i32 s9, 0, s7
	s_mul_i32 s4, s4, s53
	s_sub_i32 s1, s1, s4
	v_rcp_iflag_f32_e32 v0, v0
	s_abs_i32 s8, s1
	s_xor_b32 s4, s1, s6
	s_ashr_i32 s4, s4, 31
	v_mul_f32_e32 v0, 0x4f7ffffe, v0
	v_cvt_u32_f32_e32 v0, v0
	s_nop 0
	v_readfirstlane_b32 s10, v0
	s_mul_i32 s9, s9, s10
	s_mul_hi_u32 s9, s10, s9
	s_add_i32 s10, s10, s9
	s_mul_hi_u32 s9, s8, s10
	s_mul_i32 s10, s9, s7
	s_sub_i32 s8, s8, s10
	s_add_i32 s10, s9, 1
	s_sub_i32 s11, s8, s7
	s_cmp_ge_u32 s8, s7
	s_cselect_b32 s9, s10, s9
	s_cselect_b32 s8, s11, s8
	s_add_i32 s10, s9, 1
	s_cmp_ge_u32 s8, s7
	s_cselect_b32 s7, s10, s9
	s_xor_b32 s7, s7, s4
	s_sub_i32 s54, s7, s4
	s_mul_i32 s4, s54, s6
	s_sub_i32 s1, s1, s4
	s_add_i32 s56, s1, s5
.LBB0_373:
	s_ashr_i32 s57, s56, 31
	s_lshl_b64 s[4:5], s[56:57], 20
	s_add_u32 s58, s90, s4
	s_addc_u32 s59, s91, s5
	s_lshr_b32 s4, s101, 1
	s_lshl_b32 s4, s4, 19
	s_add_u32 s58, s58, s4
	s_addc_u32 s59, s59, 0
	s_and_b64 s[4:5], s[36:37], exec
	s_cselect_b32 s1, s59, s31
	s_cselect_b32 s4, s58, s30
	s_ashr_i32 s55, s54, 31
	s_lshl_b64 s[6:7], s[54:55], 20
	s_add_u32 s60, s67, s6
	s_addc_u32 s61, s68, s7
	s_and_b64 s[6:7], s[36:37], exec
	s_cselect_b32 s5, s61, s63
	s_cselect_b32 s6, s60, s62
	s_add_u32 s30, s30, 0x80080
	s_addc_u32 s31, s31, 0
	s_add_u32 s7, s62, 0x100
	v_mov_b32_e32 v0, 0
	s_addc_u32 s8, s63, 0
	s_mov_b32 s9, -2
	v_mov_b32_e32 v1, v0
	v_mov_b32_e32 v2, v0
	v_mov_b32_e32 v3, v0
	v_mov_b32_e32 v4, v0
	v_mov_b32_e32 v5, v0
	v_mov_b32_e32 v6, v0
	v_mov_b32_e32 v7, v0
	v_mov_b32_e32 v16, v0
	v_mov_b32_e32 v17, v0
	v_mov_b32_e32 v18, v0
	v_mov_b32_e32 v19, v0
	v_mov_b32_e32 v20, v0
	v_mov_b32_e32 v21, v0
	v_mov_b32_e32 v22, v0
	v_mov_b32_e32 v23, v0
	v_mov_b32_e32 v32, v0
	v_mov_b32_e32 v33, v0
	v_mov_b32_e32 v34, v0
	v_mov_b32_e32 v35, v0
	v_mov_b32_e32 v36, v0
	v_mov_b32_e32 v37, v0
	v_mov_b32_e32 v38, v0
	v_mov_b32_e32 v39, v0
	v_mov_b32_e32 v48, v0
	v_mov_b32_e32 v49, v0
	v_mov_b32_e32 v50, v0
	v_mov_b32_e32 v51, v0
	v_mov_b32_e32 v52, v0
	v_mov_b32_e32 v53, v0
	v_mov_b32_e32 v54, v0
	v_mov_b32_e32 v55, v0
	v_mov_b32_e32 v8, v0
	v_mov_b32_e32 v9, v0
	v_mov_b32_e32 v10, v0
	v_mov_b32_e32 v11, v0
	v_mov_b32_e32 v12, v0
	v_mov_b32_e32 v13, v0
	v_mov_b32_e32 v14, v0
	v_mov_b32_e32 v15, v0
	v_mov_b32_e32 v24, v0
	v_mov_b32_e32 v25, v0
	v_mov_b32_e32 v26, v0
	v_mov_b32_e32 v27, v0
	v_mov_b32_e32 v28, v0
	v_mov_b32_e32 v29, v0
	v_mov_b32_e32 v30, v0
	v_mov_b32_e32 v31, v0
	v_mov_b32_e32 v40, v0
	v_mov_b32_e32 v41, v0
	v_mov_b32_e32 v42, v0
	v_mov_b32_e32 v43, v0
	v_mov_b32_e32 v44, v0
	v_mov_b32_e32 v45, v0
	v_mov_b32_e32 v46, v0
	v_mov_b32_e32 v47, v0
	v_mov_b32_e32 v56, v0
	v_mov_b32_e32 v57, v0
	v_mov_b32_e32 v58, v0
	v_mov_b32_e32 v59, v0
	v_mov_b32_e32 v60, v0
	v_mov_b32_e32 v61, v0
	v_mov_b32_e32 v62, v0
	v_mov_b32_e32 v63, v0
	v_mov_b32_e32 v64, v0
	v_mov_b32_e32 v65, v0
	v_mov_b32_e32 v66, v0
	v_mov_b32_e32 v67, v0
	v_mov_b32_e32 v68, v0
	v_mov_b32_e32 v69, v0
	v_mov_b32_e32 v70, v0
	v_mov_b32_e32 v71, v0
	s_waitcnt vmcnt(0)
	v_mov_b32_e32 v80, v0
	v_mov_b32_e32 v81, v0
	v_mov_b32_e32 v82, v0
	v_mov_b32_e32 v83, v0
	v_mov_b32_e32 v86, v0
	v_mov_b32_e32 v87, v0
	v_mov_b32_e32 v88, v0
	v_mov_b32_e32 v89, v0
	v_mov_b32_e32 v98, v0
	v_mov_b32_e32 v99, v0
	v_mov_b32_e32 v100, v0
	v_mov_b32_e32 v101, v0
	v_mov_b32_e32 v102, v0
	v_mov_b32_e32 v103, v0
	v_mov_b32_e32 v104, v0
	v_mov_b32_e32 v105, v0
	v_mov_b32_e32 v114, v0
	v_mov_b32_e32 v115, v0
	v_mov_b32_e32 v116, v0
	v_mov_b32_e32 v117, v0
	v_mov_b32_e32 v118, v0
	v_mov_b32_e32 v119, v0
	v_mov_b32_e32 v120, v0
	v_mov_b32_e32 v121, v0
	v_mov_b32_e32 v72, v0
	v_mov_b32_e32 v73, v0
	v_mov_b32_e32 v74, v0
	v_mov_b32_e32 v75, v0
	v_mov_b32_e32 v76, v0
	v_mov_b32_e32 v77, v0
	v_mov_b32_e32 v78, v0
	v_mov_b32_e32 v79, v0
	v_mov_b32_e32 v90, v0
	v_mov_b32_e32 v91, v0
	v_mov_b32_e32 v92, v0
	v_mov_b32_e32 v93, v0
	v_mov_b32_e32 v94, v0
	v_mov_b32_e32 v95, v0
	v_mov_b32_e32 v96, v0
	v_mov_b32_e32 v97, v0
	v_mov_b32_e32 v106, v0
	v_mov_b32_e32 v107, v0
	v_mov_b32_e32 v108, v0
	v_mov_b32_e32 v109, v0
	v_mov_b32_e32 v110, v0
	v_mov_b32_e32 v111, v0
	v_mov_b32_e32 v112, v0
	v_mov_b32_e32 v113, v0
	v_mov_b32_e32 v122, v0
	v_mov_b32_e32 v123, v0
	v_mov_b32_e32 v124, v0
	v_mov_b32_e32 v125, v0
	v_mov_b32_e32 v126, v0
	v_mov_b32_e32 v127, v0
	v_mov_b32_e32 v128, v0
	v_mov_b32_e32 v129, v0
; #define PG8_STAGE(bufoff, gbase, voff) do { _Pragma("unroll") for (int _i = 0; _i < 2; ++_i) \
;         __builtin_amdgcn_global_load_lds((const unsigned*)((const char*)(gbase) + (voff)[_i]), (PG8_LAS unsigned*)(lds + (bufoff) + ldsw + _i * 8192), 16, 0, 0); } while (0)
; #define PG8_LDA(dst, b, h) do { _Pragma("unroll") for (int m = 0; m < 4; ++m) _Pragma("unroll") for (int k = 0; k < 2; ++k) dst[m][k] = *(const PG8_LAS bf16x8*)(lds + PG8_SA(b, h) + aoff + m * 2048 + k * 1024); } while (0)
; #define PG8_LDB(dst, b, h) do { _Pragma("unroll") for (int n = 0; n < 2; ++n) _Pragma("unroll") for (int k = 0; k < 2; ++k) dst[n][k] = *(const PG8_LAS bf16x8*)(lds + PG8_SB(b, h) + boff + n * 2048 + k * 1024); } while (0)
; #define PG8_MMA(ai, bj, At, Bt) do { __builtin_amdgcn_s_setprio(1); _Pragma("unroll") for (int m = 0; m < 4; ++m) _Pragma("unroll") for (int n = 0; n < 2; ++n) _Pragma("unroll") for (int k = 0; k < 2; ++k) \
;         acc[ai][bj][m][n] = __builtin_amdgcn_mfma_f32_16x16x32_bf16(Bt[n][k], At[m][k], acc[ai][bj][m][n], 0, 0, 0); __builtin_amdgcn_s_setprio(0); } while (0)
; #define PG8_WAIT_V(n) asm volatile("s_waitcnt vmcnt(" #n ")" ::: "memory")
; #define PG8_WAIT_L(n) asm volatile("s_waitcnt lgkmcnt(" #n ")" ::: "memory")
; #define PG8_BAR __builtin_amdgcn_s_barrier()
; #define PG8_SCHED __builtin_amdgcn_sched_barrier(0)
; template <class Epi, class Sched, bool ALIGN_EPI = false, bool SP2 = false>
; __device__ __forceinline__ void gemm_phase(PG8_LAS unsigned char* lds, const Gemm g, const Sched& S, const Epi& E, const int tid_in) {
;     ...
;             PG8_LDB(B0, 0, 0); PG8_LDB(B1, 0, 1); PG8_SCHED; PG8_LDA(At, 0, 0); PG8_STAGE(PG8_SA(1, 1), a1 + hstep, voffA);
;             PG8_WAIT_V(8); PG8_WAIT_L(0); PG8_BAR; PG8_MMA(0, 0, At, B0); PG8_MMA(0, 1, At, B1); PG8_BAR; PG8_SCHED;
;             PG8_LDA(At, 0, 1); PG8_STAGE(PG8_SB(0, 0), b2, voffB); PG8_STAGE(PG8_SB(0, 1), b2 + hstep, voffB); PG8_STAGE(PG8_SA(0, 0), a2, voffA);
;             PG8_WAIT_V(8); PG8_WAIT_L(0); PG8_BAR; PG8_MMA(1, 0, At, B0); PG8_MMA(1, 1, At, B1); PG8_BAR; PG8_SCHED;
.LBB0_374:
	s_add_u32 s10, s30, 0xfff80080
	s_addc_u32 s11, s31, -1
	s_add_i32 s12, 0, 0x10000
	s_cmp_eq_u32 s9, 28
	s_cselect_b32 s65, s1, s11
	s_cselect_b32 s64, s4, s10
	s_cselect_b32 s63, s5, s8
	s_cselect_b32 s62, s6, s7
	s_add_i32 s13, 0, 0x14000
	v_add_u32_e32 v142, s12, v196
	v_add_u32_e32 v158, s13, v196
	ds_read_b128 v[130:133], v142
	ds_read_b128 v[134:137], v142 offset:1024
	ds_read_b128 v[138:141], v142 offset:2048
	ds_read_b128 v[142:145], v142 offset:3072
	ds_read_b128 v[146:149], v158
	ds_read_b128 v[150:153], v158 offset:1024
	ds_read_b128 v[154:157], v158 offset:2048
	ds_read_b128 v[158:161], v158 offset:3072
	v_lshl_add_u64 v[194:195], s[30:31], 0, v[180:181]
	s_add_i32 m0, s69, 0xc000
	ds_read_b128 v[162:165], v199
	ds_read_b128 v[166:169], v199 offset:1024
	ds_read_b128 v[170:173], v199 offset:2048
	ds_read_b128 v[190:193], v199 offset:3072
	ds_read_b128 v[202:205], v199 offset:4096
	ds_read_b128 v[224:227], v199 offset:5120
	ds_read_b128 v[228:231], v199 offset:6144
	ds_read_b128 v[232:235], v199 offset:7168
	global_load_lds_dwordx4 v[194:195], off
	v_lshl_add_u64 v[194:195], s[30:31], 0, v[188:189]
	s_add_i32 m0, s69, 0xe000
	s_nop 0
	global_load_lds_dwordx4 v[194:195], off
	s_waitcnt vmcnt(8)
	s_waitcnt lgkmcnt(0)
	s_barrier
	s_setprio 1
	s_waitcnt lgkmcnt(0)
	v_mfma_f32_16x16x32_bf16 v[126:129], v[130:133], v[162:165], v[126:129]
	v_mfma_f32_16x16x32_bf16 v[122:125], v[138:141], v[162:165], v[122:125]
	v_mfma_f32_16x16x32_bf16 v[110:113], v[130:133], v[170:173], v[110:113]
	v_mfma_f32_16x16x32_bf16 v[106:109], v[138:141], v[170:173], v[106:109]
	v_mfma_f32_16x16x32_bf16 v[94:97], v[130:133], v[202:205], v[94:97]
	v_mfma_f32_16x16x32_bf16 v[90:93], v[138:141], v[202:205], v[90:93]
	v_mfma_f32_16x16x32_bf16 v[76:79], v[130:133], v[228:231], v[76:79]
	v_mfma_f32_16x16x32_bf16 v[72:75], v[138:141], v[228:231], v[72:75]
	v_mfma_f32_16x16x32_bf16 v[126:129], v[134:137], v[166:169], v[126:129]
	v_mfma_f32_16x16x32_bf16 v[122:125], v[142:145], v[166:169], v[122:125]
	v_mfma_f32_16x16x32_bf16 v[110:113], v[134:137], v[190:193], v[110:113]
	v_mfma_f32_16x16x32_bf16 v[106:109], v[142:145], v[190:193], v[106:109]
	v_mfma_f32_16x16x32_bf16 v[94:97], v[134:137], v[224:227], v[94:97]
	v_mfma_f32_16x16x32_bf16 v[90:93], v[142:145], v[224:227], v[90:93]
	v_mfma_f32_16x16x32_bf16 v[76:79], v[134:137], v[232:235], v[76:79]
	v_mfma_f32_16x16x32_bf16 v[72:75], v[142:145], v[232:235], v[72:75]
	s_setprio 0
	s_setprio 1
	v_mfma_f32_16x16x32_bf16 v[118:121], v[146:149], v[162:165], v[118:121]
	v_mfma_f32_16x16x32_bf16 v[114:117], v[154:157], v[162:165], v[114:117]
	v_mfma_f32_16x16x32_bf16 v[102:105], v[146:149], v[170:173], v[102:105]
	v_mfma_f32_16x16x32_bf16 v[98:101], v[154:157], v[170:173], v[98:101]
	v_mfma_f32_16x16x32_bf16 v[86:89], v[146:149], v[202:205], v[86:89]
	v_mfma_f32_16x16x32_bf16 v[80:83], v[154:157], v[202:205], v[80:83]
	v_mfma_f32_16x16x32_bf16 v[68:71], v[146:149], v[228:231], v[68:71]
	v_mfma_f32_16x16x32_bf16 v[64:67], v[154:157], v[228:231], v[64:67]
	v_mfma_f32_16x16x32_bf16 v[118:121], v[150:153], v[166:169], v[118:121]
	v_mfma_f32_16x16x32_bf16 v[114:117], v[158:161], v[166:169], v[114:117]
	v_mfma_f32_16x16x32_bf16 v[102:105], v[150:153], v[190:193], v[102:105]
	v_mfma_f32_16x16x32_bf16 v[98:101], v[158:161], v[190:193], v[98:101]
	v_mfma_f32_16x16x32_bf16 v[86:89], v[150:153], v[224:227], v[86:89]
	v_mfma_f32_16x16x32_bf16 v[80:83], v[158:161], v[224:227], v[80:83]
	v_mfma_f32_16x16x32_bf16 v[68:71], v[150:153], v[232:235], v[68:71]
	v_mfma_f32_16x16x32_bf16 v[64:67], v[158:161], v[232:235], v[64:67]
	s_setprio 0
	s_barrier
	s_add_i32 s10, s12, s66
	v_lshl_add_u64 v[194:195], s[62:63], 0, v[84:85]
	s_mov_b32 m0, s10
	ds_read_b128 v[162:165], v199 offset:16384
	ds_read_b128 v[166:169], v199 offset:17408
	ds_read_b128 v[170:173], v199 offset:18432
	ds_read_b128 v[190:193], v199 offset:19456
	ds_read_b128 v[202:205], v199 offset:20480
	ds_read_b128 v[224:227], v199 offset:21504
	ds_read_b128 v[228:231], v199 offset:22528
	ds_read_b128 v[232:235], v199 offset:23552
	global_load_lds_dwordx4 v[194:195], off
	s_add_i32 m0, s10, 0x2000
	s_add_u32 s10, s62, 0x80000
	v_lshl_add_u64 v[236:237], s[62:63], 0, v[178:179]
	s_addc_u32 s11, s63, 0
	s_add_i32 s12, s13, s66
	global_load_lds_dwordx4 v[236:237], off
	v_lshl_add_u64 v[238:239], s[10:11], 0, v[84:85]
	s_mov_b32 m0, s12
	v_lshl_add_u64 v[240:241], s[64:65], 0, v[176:177]
	global_load_lds_dwordx4 v[238:239], off
	v_lshl_add_u64 v[238:239], s[10:11], 0, v[178:179]
	s_add_i32 m0, s12, 0x2000
	s_nop 0
	global_load_lds_dwordx4 v[238:239], off
	v_lshl_add_u64 v[238:239], s[64:65], 0, v[174:175]
	s_mov_b32 m0, s69
	s_nop 0
	global_load_lds_dwordx4 v[238:239], off
	s_mov_b32 m0, s70
	s_nop 0
	global_load_lds_dwordx4 v[240:241], off
	s_waitcnt vmcnt(8)
	s_waitcnt lgkmcnt(0)
	s_barrier
	s_bitcmp1_b32 s100, 0
	s_cbranch_scc1 .Lht_skip_a
; #define PG8_STAGE(bufoff, gbase, voff) do { _Pragma("unroll") for (int _i = 0; _i < 2; ++_i) \
;         __builtin_amdgcn_global_load_lds((const unsigned*)((const char*)(gbase) + (voff)[_i]), (PG8_LAS unsigned*)(lds + (bufoff) + ldsw + _i * 8192), 16, 0, 0); } while (0)
; #define PG8_LDA(dst, b, h) do { _Pragma("unroll") for (int m = 0; m < 4; ++m) _Pragma("unroll") for (int k = 0; k < 2; ++k) dst[m][k] = *(const PG8_LAS bf16x8*)(lds + PG8_SA(b, h) + aoff + m * 2048 + k * 1024); } while (0)
; #define PG8_LDB(dst, b, h) do { _Pragma("unroll") for (int n = 0; n < 2; ++n) _Pragma("unroll") for (int k = 0; k < 2; ++k) dst[n][k] = *(const PG8_LAS bf16x8*)(lds + PG8_SB(b, h) + boff + n * 2048 + k * 1024); } while (0)
; #define PG8_MMA(ai, bj, At, Bt) do { __builtin_amdgcn_s_setprio(1); _Pragma("unroll") for (int m = 0; m < 4; ++m) _Pragma("unroll") for (int n = 0; n < 2; ++n) _Pragma("unroll") for (int k = 0; k < 2; ++k) \
;         acc[ai][bj][m][n] = __builtin_amdgcn_mfma_f32_16x16x32_bf16(Bt[n][k], At[m][k], acc[ai][bj][m][n], 0, 0, 0); __builtin_amdgcn_s_setprio(0); } while (0)
; #define PG8_WAIT_V(n) asm volatile("s_waitcnt vmcnt(" #n ")" ::: "memory")
; #define PG8_WAIT_L(n) asm volatile("s_waitcnt lgkmcnt(" #n ")" ::: "memory")
; #define PG8_BAR __builtin_amdgcn_s_barrier()
; #define PG8_SCHED __builtin_amdgcn_sched_barrier(0)
; template <class Epi, class Sched, bool ALIGN_EPI = false, bool SP2 = false>
; __device__ __forceinline__ void gemm_phase(PG8_LAS unsigned char* lds, const Gemm g, const Sched& S, const Epi& E, const int tid_in) {
;     ...
;             PG8_WAIT_V(8); PG8_WAIT_L(0); PG8_BAR; PG8_MMA(1, 0, At, B0); PG8_MMA(1, 1, At, B1); PG8_BAR; PG8_SCHED;
;             PG8_LDB(B0, 1, 0); PG8_LDB(B1, 1, 1); PG8_SCHED; PG8_LDA(At, 1, 0); PG8_STAGE(PG8_SA(0, 1), a2 + hstep, voffA);
;             PG8_WAIT_V(8); PG8_WAIT_L(0); PG8_BAR; PG8_MMA(0, 0, At, B0); PG8_MMA(0, 1, At, B1); PG8_BAR; PG8_SCHED;
	s_setprio 1
	s_waitcnt lgkmcnt(0)
	v_mfma_f32_16x16x32_bf16 v[60:63], v[130:133], v[162:165], v[60:63]
	v_mfma_f32_16x16x32_bf16 v[56:59], v[138:141], v[162:165], v[56:59]
	v_mfma_f32_16x16x32_bf16 v[44:47], v[130:133], v[170:173], v[44:47]
	v_mfma_f32_16x16x32_bf16 v[40:43], v[138:141], v[170:173], v[40:43]
	v_mfma_f32_16x16x32_bf16 v[28:31], v[130:133], v[202:205], v[28:31]
	v_mfma_f32_16x16x32_bf16 v[24:27], v[138:141], v[202:205], v[24:27]
	v_mfma_f32_16x16x32_bf16 v[12:15], v[130:133], v[228:231], v[12:15]
	v_mfma_f32_16x16x32_bf16 v[8:11], v[138:141], v[228:231], v[8:11]
	v_mfma_f32_16x16x32_bf16 v[60:63], v[134:137], v[166:169], v[60:63]
	v_mfma_f32_16x16x32_bf16 v[56:59], v[142:145], v[166:169], v[56:59]
	v_mfma_f32_16x16x32_bf16 v[44:47], v[134:137], v[190:193], v[44:47]
	v_mfma_f32_16x16x32_bf16 v[40:43], v[142:145], v[190:193], v[40:43]
	v_mfma_f32_16x16x32_bf16 v[28:31], v[134:137], v[224:227], v[28:31]
	v_mfma_f32_16x16x32_bf16 v[24:27], v[142:145], v[224:227], v[24:27]
	v_mfma_f32_16x16x32_bf16 v[12:15], v[134:137], v[232:235], v[12:15]
	v_mfma_f32_16x16x32_bf16 v[8:11], v[142:145], v[232:235], v[8:11]
	s_setprio 0
	s_setprio 1
	v_mfma_f32_16x16x32_bf16 v[52:55], v[146:149], v[162:165], v[52:55]
	v_mfma_f32_16x16x32_bf16 v[48:51], v[154:157], v[162:165], v[48:51]
	v_mfma_f32_16x16x32_bf16 v[36:39], v[146:149], v[170:173], v[36:39]
	v_mfma_f32_16x16x32_bf16 v[32:35], v[154:157], v[170:173], v[32:35]
	v_mfma_f32_16x16x32_bf16 v[20:23], v[146:149], v[202:205], v[20:23]
	v_mfma_f32_16x16x32_bf16 v[16:19], v[154:157], v[202:205], v[16:19]
	v_mfma_f32_16x16x32_bf16 v[4:7], v[146:149], v[228:231], v[4:7]
	v_mfma_f32_16x16x32_bf16 v[0:3], v[154:157], v[228:231], v[0:3]
	v_mfma_f32_16x16x32_bf16 v[52:55], v[150:153], v[166:169], v[52:55]
	v_mfma_f32_16x16x32_bf16 v[48:51], v[158:161], v[166:169], v[48:51]
	v_mfma_f32_16x16x32_bf16 v[36:39], v[150:153], v[190:193], v[36:39]
	v_mfma_f32_16x16x32_bf16 v[32:35], v[158:161], v[190:193], v[32:35]
	v_mfma_f32_16x16x32_bf16 v[20:23], v[150:153], v[224:227], v[20:23]
	v_mfma_f32_16x16x32_bf16 v[16:19], v[158:161], v[224:227], v[16:19]
	v_mfma_f32_16x16x32_bf16 v[4:7], v[150:153], v[232:235], v[4:7]
	v_mfma_f32_16x16x32_bf16 v[0:3], v[158:161], v[232:235], v[0:3]
	s_setprio 0
.Lht_skip_a:
	s_barrier
	s_add_i32 s12, 0, 0x18000
	s_add_i32 s13, 0, 0x1c000
	v_add_u32_e32 v142, s12, v196
	v_add_u32_e32 v158, s13, v196
	ds_read_b128 v[130:133], v142
	ds_read_b128 v[134:137], v142 offset:1024
	ds_read_b128 v[138:141], v142 offset:2048
	ds_read_b128 v[142:145], v142 offset:3072
	ds_read_b128 v[146:149], v158
	ds_read_b128 v[150:153], v158 offset:1024
	ds_read_b128 v[154:157], v158 offset:2048
	ds_read_b128 v[158:161], v158 offset:3072
	s_add_u32 s10, s64, 0x80000
	s_addc_u32 s11, s65, 0
	s_mov_b32 m0, s71
	v_lshl_add_u64 v[242:243], s[10:11], 0, v[174:175]
	ds_read_b128 v[162:165], v199 offset:32768
	ds_read_b128 v[166:169], v199 offset:33792
	ds_read_b128 v[170:173], v199 offset:34816
	ds_read_b128 v[190:193], v199 offset:35840
	ds_read_b128 v[202:205], v199 offset:36864
	ds_read_b128 v[224:227], v199 offset:37888
	ds_read_b128 v[228:231], v199 offset:38912
	ds_read_b128 v[232:235], v199 offset:39936
	global_load_lds_dwordx4 v[242:243], off
	v_lshl_add_u64 v[242:243], s[10:11], 0, v[176:177]
	s_mov_b32 m0, s72
	s_nop 0
	global_load_lds_dwordx4 v[242:243], off
	s_waitcnt vmcnt(8)
	s_waitcnt lgkmcnt(0)
	s_barrier
	s_setprio 1
	s_waitcnt lgkmcnt(0)
	v_mfma_f32_16x16x32_bf16 v[126:129], v[130:133], v[162:165], v[126:129]
	v_mfma_f32_16x16x32_bf16 v[122:125], v[138:141], v[162:165], v[122:125]
	v_mfma_f32_16x16x32_bf16 v[110:113], v[130:133], v[170:173], v[110:113]
	v_mfma_f32_16x16x32_bf16 v[106:109], v[138:141], v[170:173], v[106:109]
	v_mfma_f32_16x16x32_bf16 v[94:97], v[130:133], v[202:205], v[94:97]
	v_mfma_f32_16x16x32_bf16 v[90:93], v[138:141], v[202:205], v[90:93]
	v_mfma_f32_16x16x32_bf16 v[76:79], v[130:133], v[228:231], v[76:79]
	v_mfma_f32_16x16x32_bf16 v[72:75], v[138:141], v[228:231], v[72:75]
	v_mfma_f32_16x16x32_bf16 v[126:129], v[134:137], v[166:169], v[126:129]
	v_mfma_f32_16x16x32_bf16 v[122:125], v[142:145], v[166:169], v[122:125]
	v_mfma_f32_16x16x32_bf16 v[110:113], v[134:137], v[190:193], v[110:113]
	v_mfma_f32_16x16x32_bf16 v[106:109], v[142:145], v[190:193], v[106:109]
	v_mfma_f32_16x16x32_bf16 v[94:97], v[134:137], v[224:227], v[94:97]
	v_mfma_f32_16x16x32_bf16 v[90:93], v[142:145], v[224:227], v[90:93]
	v_mfma_f32_16x16x32_bf16 v[76:79], v[134:137], v[232:235], v[76:79]
	v_mfma_f32_16x16x32_bf16 v[72:75], v[142:145], v[232:235], v[72:75]
	s_setprio 0
	s_setprio 1
	v_mfma_f32_16x16x32_bf16 v[118:121], v[146:149], v[162:165], v[118:121]
	v_mfma_f32_16x16x32_bf16 v[114:117], v[154:157], v[162:165], v[114:117]
	v_mfma_f32_16x16x32_bf16 v[102:105], v[146:149], v[170:173], v[102:105]
	v_mfma_f32_16x16x32_bf16 v[98:101], v[154:157], v[170:173], v[98:101]
	v_mfma_f32_16x16x32_bf16 v[86:89], v[146:149], v[202:205], v[86:89]
	v_mfma_f32_16x16x32_bf16 v[80:83], v[154:157], v[202:205], v[80:83]
	v_mfma_f32_16x16x32_bf16 v[68:71], v[146:149], v[228:231], v[68:71]
	v_mfma_f32_16x16x32_bf16 v[64:67], v[154:157], v[228:231], v[64:67]
	v_mfma_f32_16x16x32_bf16 v[118:121], v[150:153], v[166:169], v[118:121]
	v_mfma_f32_16x16x32_bf16 v[114:117], v[158:161], v[166:169], v[114:117]
	v_mfma_f32_16x16x32_bf16 v[102:105], v[150:153], v[190:193], v[102:105]
	v_mfma_f32_16x16x32_bf16 v[98:101], v[158:161], v[190:193], v[98:101]
	v_mfma_f32_16x16x32_bf16 v[86:89], v[150:153], v[224:227], v[86:89]
	v_mfma_f32_16x16x32_bf16 v[80:83], v[158:161], v[224:227], v[80:83]
	v_mfma_f32_16x16x32_bf16 v[68:71], v[150:153], v[232:235], v[68:71]
	v_mfma_f32_16x16x32_bf16 v[64:67], v[158:161], v[232:235], v[64:67]
	s_setprio 0
	s_barrier
; #define PG8_LAS __attribute__((address_space(3)))
; #define PG8_STAGE(bufoff, gbase, voff) do { _Pragma("unroll") for (int _i = 0; _i < 2; ++_i) \
;         __builtin_amdgcn_global_load_lds((const unsigned*)((const char*)(gbase) + (voff)[_i]), (PG8_LAS unsigned*)(lds + (bufoff) + ldsw + _i * 8192), 16, 0, 0); } while (0)
; #define PG8_LDA(dst, b, h) do { _Pragma("unroll") for (int m = 0; m < 4; ++m) _Pragma("unroll") for (int k = 0; k < 2; ++k) dst[m][k] = *(const PG8_LAS bf16x8*)(lds + PG8_SA(b, h) + aoff + m * 2048 + k * 1024); } while (0)
; #define PG8_MMA(ai, bj, At, Bt) do { __builtin_amdgcn_s_setprio(1); _Pragma("unroll") for (int m = 0; m < 4; ++m) _Pragma("unroll") for (int n = 0; n < 2; ++n) _Pragma("unroll") for (int k = 0; k < 2; ++k) \
;         acc[ai][bj][m][n] = __builtin_amdgcn_mfma_f32_16x16x32_bf16(Bt[n][k], At[m][k], acc[ai][bj][m][n], 0, 0, 0); __builtin_amdgcn_s_setprio(0); } while (0)
; #define PG8_WAIT_V(n) asm volatile("s_waitcnt vmcnt(" #n ")" ::: "memory")
; #define PG8_WAIT_L(n) asm volatile("s_waitcnt lgkmcnt(" #n ")" ::: "memory")
; #define PG8_BAR __builtin_amdgcn_s_barrier()
; #define PG8_SCHED __builtin_amdgcn_sched_barrier(0)
;     __device__ __forceinline__ void operator()(const f32x4 (&acc)[2][2][4][2], const Unit& u, int wr, int wc, int fr, int fq) const {
;         const int row0 = u.pm * BM + wr * 64 + fr, col0 = u.pn * BM + wc * 32 + 8 * fq;
;         PG8_LAS float* tab = (PG8_LAS float*)(ltab + (wr * 4 + wc) * 1024);
; template <class Epi, class Sched, bool ALIGN_EPI = false, bool SP2 = false>
; __device__ __forceinline__ void gemm_phase(PG8_LAS unsigned char* lds, const Gemm g, const Sched& S, const Epi& E, const int tid_in) {
;     ...
;             PG8_LDA(At, 1, 1); PG8_STAGE(PG8_SB(1, 0), b3, voffB); PG8_STAGE(PG8_SB(1, 1), b3 + hstep, voffB); PG8_STAGE(PG8_SA(1, 0), a3, voffA);
;             PG8_WAIT_V(8); PG8_WAIT_L(0); PG8_BAR; PG8_MMA(1, 0, At, B0); PG8_MMA(1, 1, At, B1); PG8_BAR; PG8_SCHED;
	s_add_i32 s10, s12, s66
	v_lshl_add_u64 v[194:195], v[194:195], 0, s[2:3]
	s_mov_b32 m0, s10
	ds_read_b128 v[162:165], v199 offset:49152
	ds_read_b128 v[166:169], v199 offset:50176
	ds_read_b128 v[170:173], v199 offset:51200
	ds_read_b128 v[190:193], v199 offset:52224
	ds_read_b128 v[202:205], v199 offset:53248
	ds_read_b128 v[224:227], v199 offset:54272
	ds_read_b128 v[228:231], v199 offset:55296
	ds_read_b128 v[232:235], v199 offset:56320
	global_load_lds_dwordx4 v[194:195], off
	s_add_i32 m0, s10, 0x2000
	s_add_u32 s10, s62, 0x80080
	v_lshl_add_u64 v[194:195], v[236:237], 0, s[2:3]
	s_addc_u32 s11, s63, 0
	s_add_i32 s12, s13, s66
	global_load_lds_dwordx4 v[194:195], off
	v_lshl_add_u64 v[194:195], s[10:11], 0, v[84:85]
	s_mov_b32 m0, s12
	s_nop 0
	global_load_lds_dwordx4 v[194:195], off
	v_lshl_add_u64 v[194:195], s[10:11], 0, v[178:179]
	s_add_i32 m0, s12, 0x2000
	s_nop 0
	global_load_lds_dwordx4 v[194:195], off
	v_lshl_add_u64 v[194:195], v[238:239], 0, s[2:3]
	s_mov_b32 m0, s74
	s_nop 0
	global_load_lds_dwordx4 v[194:195], off
	v_lshl_add_u64 v[194:195], v[240:241], 0, s[2:3]
	s_mov_b32 m0, s75
	s_nop 0
	global_load_lds_dwordx4 v[194:195], off
	s_waitcnt vmcnt(8)
	s_waitcnt lgkmcnt(0)
	s_barrier
	s_bitcmp1_b32 s100, 0
	s_cbranch_scc1 .Lht_skip_b
	s_setprio 1
	s_waitcnt lgkmcnt(0)
	v_mfma_f32_16x16x32_bf16 v[60:63], v[130:133], v[162:165], v[60:63]
	v_mfma_f32_16x16x32_bf16 v[56:59], v[138:141], v[162:165], v[56:59]
	v_mfma_f32_16x16x32_bf16 v[44:47], v[130:133], v[170:173], v[44:47]
	v_mfma_f32_16x16x32_bf16 v[40:43], v[138:141], v[170:173], v[40:43]
	v_mfma_f32_16x16x32_bf16 v[28:31], v[130:133], v[202:205], v[28:31]
	v_mfma_f32_16x16x32_bf16 v[24:27], v[138:141], v[202:205], v[24:27]
	v_mfma_f32_16x16x32_bf16 v[12:15], v[130:133], v[228:231], v[12:15]
	v_mfma_f32_16x16x32_bf16 v[8:11], v[138:141], v[228:231], v[8:11]
	v_mfma_f32_16x16x32_bf16 v[60:63], v[134:137], v[166:169], v[60:63]
	v_mfma_f32_16x16x32_bf16 v[56:59], v[142:145], v[166:169], v[56:59]
	v_mfma_f32_16x16x32_bf16 v[44:47], v[134:137], v[190:193], v[44:47]
	v_mfma_f32_16x16x32_bf16 v[40:43], v[142:145], v[190:193], v[40:43]
	v_mfma_f32_16x16x32_bf16 v[28:31], v[134:137], v[224:227], v[28:31]
	v_mfma_f32_16x16x32_bf16 v[24:27], v[142:145], v[224:227], v[24:27]
	v_mfma_f32_16x16x32_bf16 v[12:15], v[134:137], v[232:235], v[12:15]
	v_mfma_f32_16x16x32_bf16 v[8:11], v[142:145], v[232:235], v[8:11]
	s_setprio 0
	s_setprio 1
	v_mfma_f32_16x16x32_bf16 v[52:55], v[146:149], v[162:165], v[52:55]
	v_mfma_f32_16x16x32_bf16 v[48:51], v[154:157], v[162:165], v[48:51]
	v_mfma_f32_16x16x32_bf16 v[36:39], v[146:149], v[170:173], v[36:39]
	v_mfma_f32_16x16x32_bf16 v[32:35], v[154:157], v[170:173], v[32:35]
	v_mfma_f32_16x16x32_bf16 v[20:23], v[146:149], v[202:205], v[20:23]
	v_mfma_f32_16x16x32_bf16 v[16:19], v[154:157], v[202:205], v[16:19]
	v_mfma_f32_16x16x32_bf16 v[4:7], v[146:149], v[228:231], v[4:7]
	v_mfma_f32_16x16x32_bf16 v[0:3], v[154:157], v[228:231], v[0:3]
	v_mfma_f32_16x16x32_bf16 v[52:55], v[150:153], v[166:169], v[52:55]
	v_mfma_f32_16x16x32_bf16 v[48:51], v[158:161], v[166:169], v[48:51]
	v_mfma_f32_16x16x32_bf16 v[36:39], v[150:153], v[190:193], v[36:39]
	v_mfma_f32_16x16x32_bf16 v[32:35], v[158:161], v[190:193], v[32:35]
	v_mfma_f32_16x16x32_bf16 v[20:23], v[150:153], v[224:227], v[20:23]
	v_mfma_f32_16x16x32_bf16 v[16:19], v[158:161], v[224:227], v[16:19]
	v_mfma_f32_16x16x32_bf16 v[4:7], v[150:153], v[232:235], v[4:7]
	v_mfma_f32_16x16x32_bf16 v[0:3], v[158:161], v[232:235], v[0:3]
	s_setprio 0
.Lht_skip_b:
	s_barrier
	s_add_i32 s9, s9, 2
	s_add_u32 s30, s30, 0x100
	s_addc_u32 s31, s31, 0
	s_add_u32 s7, s7, 0x100
	s_addc_u32 s8, s8, 0
	s_cmp_gt_u32 s9, 29
	s_cbranch_scc0 .LBB0_374
	s_and_b64 vcc, exec, s[48:49]
	s_cbranch_vccz .LBB0_377
	s_barrier
.LBB0_377:
	s_lshl_b32 s4, s38, 8
	s_add_i32 s4, s4, s73
	s_lshr_b32 s5, s100, 1
	s_lshl_b32 s5, s5, 7
	s_add_i32 s4, s4, s5
	s_lshl_b32 s5, s5, 2
	v_add_u32_e32 v201, s5, v201
	v_lshl_or_b32 v190, s0, 8, v197
	s_mov_b64 s[0:1], -1
	s_and_b64 vcc, exec, s[46:47]
	s_cbranch_vccnz .LBB0_381
	s_and_b64 vcc, exec, s[0:1]
	s_cbranch_vccnz .LBB0_384

; __device__ __forceinline__ unsigned cvt_pk_bf16(float lo, float hi) { cvt_f32x2_t v = {lo, hi}; cvt_bf16x2_t b = __builtin_convertvector(v, cvt_bf16x2_t); return __builtin_bit_cast(unsigned, b); }
;     __device__ __forceinline__ void operator()(const f32x4 (&acc)[2][2][4][2], const Unit& u, int wr, int wc, int fr, int fq) const {
;     ...
;                 float rs = 1.f, t = 0.f; if (ln) { const float mu = tab[(ai * 64 + m * 16 + fr) * 2]; rs = tab[(ai * 64 + m * 16 + fr) * 2 + 1]; t = -rs * mu; }
; #pragma unroll
;                 for (int bj = 0; bj < 2; ++bj) { f32x4 v0 = acc[ai][bj][m][0], v1 = acc[ai][bj][m][1];
;                     if (ln) { v0 = v0 * rs + (cv[bj][0] * t + dv[bj][0]); v1 = v1 * rs + (cv[bj][1] * t + dv[bj][1]); }
;                     u32x4 w; w.x = cvt_pk_bf16(v0[0], v0[1]); w.y = cvt_pk_bf16(v0[2], v0[3]); w.z = cvt_pk_bf16(v1[0], v1[1]); w.w = cvt_pk_bf16(v1[2], v1[3]);
;                     *(u32x4*)(rowp + bj * HALF) = w; } }
.LBB0_407:
	v_cvt_pk_bf16_f32 v68, v68, v69
	v_cvt_pk_bf16_f32 v69, v70, v71
	v_cvt_pk_bf16_f32 v70, v64, v65
	v_cvt_pk_bf16_f32 v71, v66, v67
	s_bitcmp1_b32 s100, 0
	s_cbranch_scc1 .Lht_epi_done
	s_and_b64 vcc, exec, s[38:39]
	global_store_dwordx4 v[86:87], v[68:71], off offset:256
	s_cbranch_vccnz .LBB0_409
	ds_read_b64 v[64:65], v201 offset:512
	s_waitcnt lgkmcnt(0)
	v_mul_f32_e64 v66, v64, -v65
	v_mov_b32_e32 v64, v65
	v_mov_b32_e32 v65, v64
	s_and_b64 vcc, exec, s[38:39]
	v_mov_b32_e32 v67, v66
	s_cbranch_vccz .LBB0_410
	s_branch .LBB0_411

;     __device__ __forceinline__ void operator()(const f32x4 (&acc)[2][2][4][2], const Unit& u, int wr, int wc, int fr, int fq) const {
;     ...
;                     *(u32x4*)(rowp + bj * HALF) = w; } }
; template <class Epi, class Sched, bool ALIGN_EPI = false, bool SP2 = false>
; __device__ __forceinline__ void gemm_phase(PG8_LAS unsigned char* lds, const Gemm g, const Sched& S, const Epi& E, const int tid_in) {
;     ...
;         if constexpr (!Epi::AFTER_DRAIN) { E(acc, cur, wr, wc, fr, fq); S.done(cur); }
;         if (!has_next) break;
.Lht_epi_done:
	global_store_dwordx4 v[86:87], v[68:71], off offset:256
	s_mov_b64 s[0:1], -1
	s_branch .LBB0_370

; __global__ void __launch_bounds__(512, 2) fwd_kernel(Args a) {
	.amdhsa_kernel _Z10fwd_kernel4Args
		.amdhsa_group_segment_fixed_size 0
		.amdhsa_private_segment_fixed_size 0
		.amdhsa_kernarg_size 464
		.amdhsa_user_sgpr_count 2
		.amdhsa_user_sgpr_dispatch_ptr 0
		.amdhsa_user_sgpr_queue_ptr 0
		.amdhsa_user_sgpr_kernarg_segment_ptr 1
		.amdhsa_user_sgpr_dispatch_id 0
		.amdhsa_user_sgpr_kernarg_preload_length 0
		.amdhsa_user_sgpr_kernarg_preload_offset 0
		.amdhsa_user_sgpr_private_segment_size 0
		.amdhsa_uses_dynamic_stack 0
		.amdhsa_enable_private_segment 0
		.amdhsa_system_sgpr_workgroup_id_x 1
		.amdhsa_system_sgpr_workgroup_id_y 0
		.amdhsa_system_sgpr_workgroup_id_z 0
		.amdhsa_system_sgpr_workgroup_info 0
		.amdhsa_system_vgpr_workitem_id 2
		.amdhsa_next_free_vgpr 256
		.amdhsa_next_free_sgpr 102
		.amdhsa_accum_offset 256
		.amdhsa_reserve_vcc 1
		.amdhsa_float_round_mode_32 0
		.amdhsa_float_round_mode_16_64 0
		.amdhsa_float_denorm_mode_32 3
		.amdhsa_float_denorm_mode_16_64 3
		.amdhsa_dx10_clamp 1
		.amdhsa_ieee_mode 1
		.amdhsa_fp16_overflow 0
		.amdhsa_tg_split 0
		.amdhsa_exception_fp_ieee_invalid_op 0
		.amdhsa_exception_fp_denorm_src 0
		.amdhsa_exception_fp_ieee_div_zero 0
		.amdhsa_exception_fp_ieee_overflow 0
		.amdhsa_exception_fp_ieee_underflow 0
		.amdhsa_exception_fp_ieee_inexact 0
		.amdhsa_exception_int_div_zero 0
	.end_amdhsa_kernel

; __global__ void __launch_bounds__(512, 2) fwd_kernel(Args a) {
amdhsa.kernels:
  - .agpr_count:     0
    .args:
      - .offset:         0
        .size:           208
        .value_kind:     by_value
      - .offset:         208
        .size:           4
        .value_kind:     hidden_block_count_x
      - .offset:         212
        .size:           4
        .value_kind:     hidden_block_count_y
      - .offset:         216
        .size:           4
        .value_kind:     hidden_block_count_z
      - .offset:         220
        .size:           2
        .value_kind:     hidden_group_size_x
      - .offset:         222
        .size:           2
        .value_kind:     hidden_group_size_y
      - .offset:         224
        .size:           2
        .value_kind:     hidden_group_size_z
      - .offset:         226
        .size:           2
        .value_kind:     hidden_remainder_x
      - .offset:         228
        .size:           2
        .value_kind:     hidden_remainder_y
      - .offset:         230
        .size:           2
        .value_kind:     hidden_remainder_z
      - .offset:         248
        .size:           8
        .value_kind:     hidden_global_offset_x
      - .offset:         256
        .size:           8
        .value_kind:     hidden_global_offset_y
      - .offset:         264
        .size:           8
        .value_kind:     hidden_global_offset_z
      - .offset:         272
        .size:           2
        .value_kind:     hidden_grid_dims
      - .offset:         296
        .size:           8
        .value_kind:     hidden_multigrid_sync_arg
      - .offset:         328
        .size:           4
        .value_kind:     hidden_dynamic_lds_size
    .group_segment_fixed_size: 0
    .kernarg_segment_align: 8
    .kernarg_segment_size: 464
    .language:       OpenCL C
    .language_version:
      - 2
      - 0
    .max_flat_workgroup_size: 512
    .name:           _Z10fwd_kernel4Args
    .private_segment_fixed_size: 0
    .sgpr_count:     108
    .sgpr_spill_count: 221
    .symbol:         _Z10fwd_kernel4Args.kd
    .uniform_work_group_size: 1
    .uses_dynamic_stack: false
    .vgpr_count:     256
    .vgpr_spill_count: 0
    .wavefront_size: 64
